# P9: L2 touch-prefetch of next channel PT rows and next FFT-kernel GR rows at top of each pp iteration
# baseline (speedup 1.0000x reference)
.LBB0_1794:
	s_add_u32 s98, s78, 0x4000000
	v_subrev_u32_e32 v252, s98, v160
	s_add_i32 s98, s44, s33
	s_cmpk_gt_i32 s98, 0x3ff
	s_cbranch_scc1 .Lp9_nopt
	s_mov_b32 s100, s98
	s_ashr_i32 s101, s98, 31
	s_lshl_b64 s[100:101], s[100:101], 13
	s_add_u32 s100, s100, s78
	s_addc_u32 s101, s101, s79
	s_add_u32 s100, s100, 0x4000000
	s_addc_u32 s101, s101, 0
	global_load_dword v253, v252, s[100:101]
	s_add_u32 s100, s100, 0x2000000
	s_addc_u32 s101, s101, 0
	global_load_dword v253, v252, s[100:101]
	s_add_u32 s100, s100, 0x2000000
	s_addc_u32 s101, s101, 0
	global_load_dword v253, v252, s[100:101]
	s_add_u32 s100, s100, 0x2000000
	s_addc_u32 s101, s101, 0
	global_load_dword v253, v252, s[100:101]
	s_add_u32 s100, s100, 0x2000000
	s_addc_u32 s101, s101, 0
	global_load_dword v253, v252, s[100:101]
	s_add_u32 s100, s100, 0x2000000
	s_addc_u32 s101, s101, 0
	global_load_dword v253, v252, s[100:101]
	s_add_u32 s100, s100, 0x2000000
	s_addc_u32 s101, s101, 0
	global_load_dword v253, v252, s[100:101]
	s_add_u32 s100, s100, 0x2000000
	s_addc_u32 s101, s101, 0
	global_load_dword v253, v252, s[100:101]
.Lp9_nopt:
	v_lshlrev_b32_e32 v252, 1, v252
	s_add_i32 s98, s44, 0x400
	s_mov_b32 s100, s98
	s_ashr_i32 s101, s98, 31
	s_lshl_b64 s[100:101], s[100:101], 14
	s_add_u32 s100, s100, s78
	s_addc_u32 s101, s101, s79
	s_add_u32 s100, s100, 0x1600000
	s_addc_u32 s101, s101, 0
	global_load_dword v253, v252, s[100:101]
	s_add_i32 s98, s44, s33
	s_cmpk_gt_i32 s98, 0x3ff
	s_cbranch_scc1 .Lp9_nogr
	s_mov_b32 s100, s98
	s_ashr_i32 s101, s98, 31
	s_lshl_b64 s[100:101], s[100:101], 14
	s_add_u32 s100, s100, s78
	s_addc_u32 s101, s101, s79
	s_add_u32 s100, s100, 0x1600000
	s_addc_u32 s101, s101, 0
	global_load_dword v253, v252, s[100:101]
